# bh2 + GEMM phases: one static s_setprio 1 for waves 4-7 (lagging group), per-segment flips deleted
# speedup vs baseline: 1.0045x; 1.0011x over previous
; template <class Epi, class Sched, bool SEG3 = false>
; __device__ __forceinline__ void gemm_phase(PG8_LAS unsigned char* lds, const Gemm g, const Sched& S, const Epi& E) {
;     ...
;     const int tid = tid_, wid = __builtin_amdgcn_readfirstlane(tid >> 6), lane = tid & 63, wr = wid >> 2, wc = wid & 3, fr = lane & 15, fq = lane >> 4;
.LBB0_413:
	s_mov_b32 s98, 0
	v_readfirstlane_b32 s99, v0
	s_nop 3
	s_lshr_b32 s99, s99, 6
	s_cmp_ge_u32 s99, 4
	s_cbranch_scc0 .Lprio_done_4
	s_setprio 1

; #define SUB(k, bit) (!(kargs()->li == 1 && (k) == lo) || ((kargs()->submask >> (bit)) & 1u))
; __global__ void __launch_bounds__(NWAVES * 64, 2) fwd(Args args_unused) {
;     ...
;         if (IN(pb + 3)) {
;             PH_PTRS PH_LAYER
;             if (SUB(pb + 3, 0)) {
;                 const int nitems = (M / 16) * 5;
.LBB0_1364:
	s_setprio 0
	v_readlane_b32 s99, v254, 3
	s_nop 3
	s_lshr_b32 s99, s99, 3
	s_and_b32 s99, s99, 3
	s_mov_b32 s98, 2
	s_cmp_eq_u32 s99, 1
	s_cselect_b32 s98, 0, s98
	s_cmp_eq_u32 s99, 2
	s_cselect_b32 s98, 0, s98
	s_cmp_eq_u32 s99, 3
	s_cselect_b32 s98, 0, s98

; __global__ void __launch_bounds__(NWAVES * 64, 2) fwd(Args args_unused) {
;     ...
;     if (IN(PH_FINAL)) {
;         PH_PTRS
;         const float* gvec = A->in[I_GFIN];
;         f32x4 gv[4];
; #pragma unroll
;         for (int j = 0; j < 4; ++j) gv[j] = *(const f32x4*)(gvec + 4 * (lane + 64 * j));
;         for (int row0 = gw; row0 < M; row0 += 4 * NGW) {
;             v2u xw_[4][4];
; #pragma unroll
;             for (int k = 0; k < 4; ++k) { const int row = row0 + k * NGW;
; #pragma unroll
;                 for (int j = 0; j < 4; ++j) { xw_[k][j] = (v2u){0u, 0u}; if (row < M) xw_[k][j] = *(const v2u*)(X + (size_t)row * DM + 4 * (lane + 64 * j)); } }
.LBB0_4462:
	s_setprio 0
	s_cmp_lt_i32 s84, 24
	s_cselect_b64 s[0:1], -1, 0
	s_cmp_gt_i32 s85, 23
	s_cselect_b64 s[4:5], -1, 0
	s_and_b64 s[0:1], s[0:1], s[4:5]
	s_and_b64 vcc, exec, s[0:1]
	s_cbranch_vccz .LBB0_4512
	s_mov_b32 s0, 0
	v_readlane_b32 s1, v254, 3
	v_readlane_b32 s0, v254, 2
	s_lshl_b32 s16, s1, 3
	s_mov_b32 s7, 0
	v_writelane_b32 v254, s0, 2
	v_readfirstlane_b32 s0, v0
	s_ashr_i32 s4, s0, 6
	s_add_i32 s12, s4, s16
	s_cmp_gt_i32 s12, 0x80ff
	s_cbranch_scc1 .LBB0_4512
	s_load_dwordx2 s[8:9], s[82:83], 0x138
	s_load_dwordx4 s[0:3], s[82:83], 0x140
	v_lshlrev_b32_e32 v1, 2, v0
	v_and_b32_e32 v18, 0xfc, v1
	v_lshlrev_b32_e32 v20, 2, v18
	s_waitcnt lgkmcnt(0)
	global_load_dwordx4 v[2:5], v20, s[8:9]
	global_load_dwordx4 v[6:9], v20, s[8:9] offset:1024
	global_load_dwordx4 v[10:13], v20, s[8:9] offset:2048
	global_load_dwordx4 v[14:17], v20, s[8:9] offset:3072
	v_mbcnt_lo_u32_b32 v1, -1, 0
	v_mbcnt_hi_u32_b32 v1, -1, v1
	v_and_b32_e32 v19, 64, v1
	v_add_u32_e32 v22, 64, v19
	v_xor_b32_e32 v19, 1, v1
	v_cmp_lt_i32_e32 vcc, v19, v22
	v_xor_b32_e32 v23, 2, v1
	v_readlane_b32 s18, v254, 2
	v_cndmask_b32_e32 v19, v1, v19, vcc
	v_cmp_lt_i32_e32 vcc, v23, v22
	s_lshl_b32 s33, s18, 3
	s_add_u32 s38, s2, 0xcf00000
	v_cndmask_b32_e32 v23, v1, v23, vcc
	v_lshlrev_b32_e32 v54, 2, v23
	v_xor_b32_e32 v23, 4, v1
	v_cmp_lt_i32_e32 vcc, v23, v22
	v_mov_b32_e32 v21, 0
	s_addc_u32 s39, s3, 0
	v_cndmask_b32_e32 v23, v1, v23, vcc
	v_lshlrev_b32_e32 v55, 2, v23
	v_xor_b32_e32 v23, 8, v1
	v_cmp_lt_i32_e32 vcc, v23, v22
	s_ashr_i32 s5, s4, 31
	s_ashr_i32 s17, s16, 31
	v_cndmask_b32_e32 v23, v1, v23, vcc
	v_lshlrev_b32_e32 v56, 2, v23
	v_xor_b32_e32 v23, 16, v1
	v_cmp_lt_i32_e32 vcc, v23, v22
	s_lshl_b32 s8, s18, 5
	s_add_i32 s6, s12, 0xffff8000
	v_cndmask_b32_e32 v23, v1, v23, vcc
	v_lshlrev_b32_e32 v57, 2, v23
	v_xor_b32_e32 v23, 32, v1
	v_cmp_lt_i32_e32 vcc, v23, v22
	s_lshl_b64 s[10:11], s[16:17], 10
	v_and_b32_e32 v0, 63, v0
	v_cndmask_b32_e32 v1, v1, v23, vcc
	v_lshl_add_u64 v[22:23], s[0:1], 0, v[20:21]
	s_lshl_b64 s[0:1], s[4:5], 10
	s_add_u32 s40, s0, s10
	s_addc_u32 s41, s1, s11
	s_add_i32 s0, s12, s33
	s_ashr_i32 s9, s8, 31
	s_ashr_i32 s1, s0, 31
	s_lshl_b64 s[10:11], s[8:9], 10
	s_lshl_b64 s[12:13], s[0:1], 11
	s_add_u32 s12, s2, s12
	s_addc_u32 s13, s3, s13
	s_lshl_b64 s[14:15], s[8:9], 11
	s_add_u32 s4, s4, s16
	s_addc_u32 s5, s5, s17
	s_lshl_b64 s[4:5], s[4:5], 11
	s_add_u32 s2, s2, s4
	s_addc_u32 s3, s3, s5
	s_add_u32 s16, s2, 0xcf00400
	v_lshlrev_b32_e32 v19, 2, v19
	v_lshlrev_b32_e32 v58, 2, v1
	v_lshlrev_b32_e32 v20, 3, v0
	s_addc_u32 s17, s3, 0
	s_lshl_b32 s9, s18, 4
	s_mul_i32 s42, s18, 24
	s_lshl_b64 s[18:19], s[0:1], 10
	s_mov_b64 s[20:21], 0
	v_mov_b32_e32 v59, 0x358637bd
	s_branch .LBB0_4467
